# SWIGLU epilogue in two 32-row passes through stage-1 LDS areas; next tile's first K-tile is LDS-DMA staged into stage-0 areas during the epilogue, tile prologue skips that load
# speedup vs baseline: 1.0318x; 1.0082x over previous
; #define LAS __attribute__((address_space(3)))
; DI unsigned xb_add(unsigned* p, unsigned v) { return __hip_atomic_fetch_add(p, v, __ATOMIC_RELAXED, __HIP_MEMORY_SCOPE_AGENT); }
; DI unsigned xb_xcc_id() { return (unsigned)__builtin_amdgcn_s_getreg((3 << 11) | 20) & 0xFu; }
; DI XcdBarrier xcd_barrier_post(unsigned* bar, volatile LAS unsigned* st) {
;   XcdBarrier b; b.bar = bar; b.x = xb_xcc_id(); b.st = st;
;   if (threadIdx.x == 0) (void)xb_add(&bar[XB_XCNT(b.x)], 1u);
;   return b;
; __global__ void __launch_bounds__(NT, 2) mega(Params p) {
;   cg::grid_group grid = cg::this_grid();
;   __shared__ __attribute__((aligned(16))) char smem[SMEM_BYTES];
;   __shared__ __attribute__((aligned(16))) unsigned xb_words[4];
;   if (threadIdx.x < 4) xb_words[threadIdx.x] = 0u;
;   __syncthreads();
;   const XcdBarrier xb = xcd_barrier_post((unsigned*)(p.ws + OFF_BAR), (volatile LAS unsigned*)xb_words);
_Z4mega6Params:
	v_writelane_b32 v255, 0, 51
	s_load_dwordx4 s[24:27], s[0:1], 0xc0
	s_load_dword s20, s[0:1], 0xd0
	v_writelane_b32 v252, s2, 0
	v_and_b32_e32 v210, 0x3ff, v0
	v_cmp_gt_u32_e32 vcc, 4, v210
	v_writelane_b32 v252, s3, 1
	s_add_u32 s2, s0, 0xc8
	s_addc_u32 s3, s1, 0
	v_writelane_b32 v252, s2, 2
	s_nop 1
	v_writelane_b32 v252, s3, 3
	s_and_saveexec_b64 s[2:3], vcc
	v_mov_b32_e32 v1, 0x24400
	v_lshl_add_u32 v1, v210, 2, v1
	v_mov_b32_e32 v2, 0
	ds_write_b32 v1, v2
	s_or_b64 exec, exec, s[2:3]
	s_waitcnt lgkmcnt(0)
	s_barrier
	s_add_u32 s4, s24, 0x161ed000
	s_getreg_b32 s2, hwreg(HW_REG_XCC_ID, 0, 4)
	s_addc_u32 s5, s25, 0
	s_and_b32 s21, s2, 15
	v_readlane_b32 s2, v252, 0
	v_readlane_b32 s3, v252, 1
	s_mov_b32 s3, 0
	v_writelane_b32 v252, s2, 0
	v_cmp_eq_u32_e64 s[6:7], 0, v210
	s_nop 0
	v_writelane_b32 v252, s3, 1
	s_mov_b64 s[2:3], exec
	v_writelane_b32 v252, s6, 4
	s_nop 1
	v_writelane_b32 v252, s7, 5
	s_and_b64 s[6:7], s[2:3], s[6:7]
	s_mov_b64 exec, s[6:7]
	s_cbranch_execz .LBB0_5
	s_mov_b64 s[6:7], exec
	v_mbcnt_lo_u32_b32 v1, s6, 0
	v_mbcnt_hi_u32_b32 v1, s7, v1
	v_cmp_eq_u32_e32 vcc, 0, v1
	s_and_b64 s[8:9], exec, vcc
	s_mov_b64 exec, s[8:9]
	s_cbranch_execz .LBB0_5
	s_lshl_b32 s8, s21, 8
	s_bcnt1_i32_b64 s6, s[6:7]
	v_mov_b32_e32 v1, s8
	v_mov_b32_e32 v2, s6
	global_atomic_add v1, v2, s[4:5] offset:1024

; DI void lds_barrier() { asm volatile("s_waitcnt lgkmcnt(0)\n\ts_barrier" ::: "memory"); }
; #define G_LOAD(RA, RB, KT) { size_t as_ = astep, bs_ = bstep; asm volatile("" : "+s"(as_), "+s"(bs_)); \
;       _Pragma("unroll") for (int i = 0; i < 4; ++i) { RA[i] = *(const u32x4*)(Ag + i * as_ + (KT) * 64); RB[i] = *(const u32x4*)(Bg + i * bs_ + (KT) * 64); } }
; DI void gemm_run(const GemmCfg c, char* smem, float* const g_h, u16* const g_hb, float* const g_out, const int final_out) {
;     ...
;     f32x16 acc[2][4];
; #pragma unroll
;     for (int a = 0; a < 2; ++a)
; #pragma unroll
;       for (int b = 0; b < 4; ++b)
; #pragma unroll
;         for (int i = 0; i < 16; ++i) acc[a][b][i] = 0.f;
;     float ss[4] = {0.f, 0.f, 0.f, 0.f};
;     u32x4 ra0[4], rb0[4];
;     ...
;     G_LOAD(ra0, rb0, 0);
;     __syncthreads();
;     G_STORE(ra0, rb0, 0);
;     G_LOAD(ra0, rb0, 1);
;     lds_barrier();
.Lgemm_rz_skip:
	v_readlane_b32 s0, v255, 51
	s_nop 1
	s_cmp_lg_u32 s0, 0
	s_cbranch_scc1 .Lgemm_pf_skip
	s_add_u32 m0, s8, 0x0
	s_nop 0
	global_load_lds_dwordx4 v130, s[4:5]
	s_add_u32 m0, s8, 0x12000
	s_nop 0
	global_load_lds_dwordx4 v134, s[6:7]
	s_add_u32 m0, s8, 0x400
	s_nop 0
	global_load_lds_dwordx4 v131, s[4:5]
	s_add_u32 m0, s8, 0x12400
	s_nop 0
	global_load_lds_dwordx4 v135, s[6:7]
	s_add_u32 m0, s8, 0x800
	s_nop 0
	global_load_lds_dwordx4 v132, s[4:5]
	s_add_u32 m0, s8, 0x12800
	s_nop 0
	global_load_lds_dwordx4 v136, s[6:7]
	s_add_u32 m0, s8, 0xc00
	s_nop 0
	global_load_lds_dwordx4 v133, s[4:5]
	s_add_u32 m0, s8, 0x12c00
	s_nop 0
	global_load_lds_dwordx4 v137, s[6:7]
.Lgemm_pf_skip:
	s_mov_b32 s0, 0
	s_nop 0
	v_writelane_b32 v255, s0, 51
	s_add_u32 s4, s4, 0x80
	s_addc_u32 s5, s5, 0
	s_add_u32 s6, s6, 0x80
	s_addc_u32 s7, s7, 0
	s_add_u32 m0, s8, 0x9000
	s_nop 0
	global_load_lds_dwordx4 v130, s[4:5]
	s_add_u32 m0, s8, 0x1b000
	s_nop 0
	global_load_lds_dwordx4 v134, s[6:7]
	s_add_u32 m0, s8, 0x9400
	s_nop 0
	global_load_lds_dwordx4 v131, s[4:5]
	s_add_u32 m0, s8, 0x1b400
	s_nop 0
	global_load_lds_dwordx4 v135, s[6:7]
	s_add_u32 m0, s8, 0x9800
	s_nop 0
	global_load_lds_dwordx4 v132, s[4:5]
	s_add_u32 m0, s8, 0x1b800
	s_nop 0
	global_load_lds_dwordx4 v136, s[6:7]
	s_add_u32 m0, s8, 0x9c00
	s_nop 0
	global_load_lds_dwordx4 v133, s[4:5]
	s_add_u32 m0, s8, 0x1bc00
	s_nop 0
	global_load_lds_dwordx4 v137, s[6:7]
	s_add_u32 s4, s4, 0x80
	s_addc_u32 s5, s5, 0
	s_add_u32 s6, s6, 0x80
	s_addc_u32 s7, s7, 0
	v_mov_b32_e32 v0, 0
	v_mov_b32_e32 v1, 0
	v_mov_b32_e32 v2, 0
	v_mov_b32_e32 v3, 0
	v_mov_b32_e32 v4, 0
	v_mov_b32_e32 v5, 0
	v_mov_b32_e32 v6, 0
	v_mov_b32_e32 v7, 0
	v_mov_b32_e32 v8, 0
	v_mov_b32_e32 v9, 0
	v_mov_b32_e32 v10, 0
	v_mov_b32_e32 v11, 0
	v_mov_b32_e32 v12, 0
	v_mov_b32_e32 v13, 0
	v_mov_b32_e32 v14, 0
	v_mov_b32_e32 v15, 0
	v_mov_b32_e32 v16, 0
	v_mov_b32_e32 v17, 0
	v_mov_b32_e32 v18, 0
	v_mov_b32_e32 v19, 0
	v_mov_b32_e32 v20, 0
	v_mov_b32_e32 v21, 0
	v_mov_b32_e32 v22, 0
	v_mov_b32_e32 v23, 0
	v_mov_b32_e32 v24, 0
	v_mov_b32_e32 v25, 0
	v_mov_b32_e32 v26, 0
	v_mov_b32_e32 v27, 0
	v_mov_b32_e32 v28, 0
	v_mov_b32_e32 v29, 0
	v_mov_b32_e32 v30, 0
	v_mov_b32_e32 v31, 0
	v_mov_b32_e32 v32, 0
	v_mov_b32_e32 v33, 0
	v_mov_b32_e32 v34, 0
	v_mov_b32_e32 v35, 0
	v_mov_b32_e32 v36, 0
	v_mov_b32_e32 v37, 0
	v_mov_b32_e32 v38, 0
	v_mov_b32_e32 v39, 0
	v_mov_b32_e32 v40, 0
	v_mov_b32_e32 v41, 0
	v_mov_b32_e32 v42, 0
	v_mov_b32_e32 v43, 0
	v_mov_b32_e32 v44, 0
	v_mov_b32_e32 v45, 0
	v_mov_b32_e32 v46, 0
	v_mov_b32_e32 v47, 0
	v_mov_b32_e32 v48, 0
	v_mov_b32_e32 v49, 0
	v_mov_b32_e32 v50, 0
	v_mov_b32_e32 v51, 0
	v_mov_b32_e32 v52, 0
	v_mov_b32_e32 v53, 0
	v_mov_b32_e32 v54, 0
	v_mov_b32_e32 v55, 0
	v_mov_b32_e32 v56, 0
	v_mov_b32_e32 v57, 0
	v_mov_b32_e32 v58, 0
	v_mov_b32_e32 v59, 0
	v_mov_b32_e32 v60, 0
	v_mov_b32_e32 v61, 0
	v_mov_b32_e32 v62, 0
	v_mov_b32_e32 v63, 0
	v_mov_b32_e32 v64, 0
	v_mov_b32_e32 v65, 0
	v_mov_b32_e32 v66, 0
	v_mov_b32_e32 v67, 0
	v_mov_b32_e32 v68, 0
	v_mov_b32_e32 v69, 0
	v_mov_b32_e32 v70, 0
	v_mov_b32_e32 v71, 0
	v_mov_b32_e32 v72, 0
	v_mov_b32_e32 v73, 0
	v_mov_b32_e32 v74, 0
	v_mov_b32_e32 v75, 0
	v_mov_b32_e32 v76, 0
	v_mov_b32_e32 v77, 0
	v_mov_b32_e32 v78, 0
	v_mov_b32_e32 v79, 0
	v_mov_b32_e32 v80, 0
	v_mov_b32_e32 v81, 0
	v_mov_b32_e32 v82, 0
	v_mov_b32_e32 v83, 0
	v_mov_b32_e32 v84, 0
	v_mov_b32_e32 v85, 0
	v_mov_b32_e32 v86, 0
	v_mov_b32_e32 v87, 0
	v_mov_b32_e32 v88, 0
	v_mov_b32_e32 v89, 0
	v_mov_b32_e32 v90, 0
	v_mov_b32_e32 v91, 0
	v_mov_b32_e32 v92, 0
	v_mov_b32_e32 v93, 0
	v_mov_b32_e32 v94, 0
	v_mov_b32_e32 v95, 0
	v_mov_b32_e32 v96, 0
	v_mov_b32_e32 v97, 0
	v_mov_b32_e32 v98, 0
	v_mov_b32_e32 v99, 0
	v_mov_b32_e32 v100, 0
	v_mov_b32_e32 v101, 0
	v_mov_b32_e32 v102, 0
	v_mov_b32_e32 v103, 0
	v_mov_b32_e32 v104, 0
	v_mov_b32_e32 v105, 0
	v_mov_b32_e32 v106, 0
	v_mov_b32_e32 v107, 0
	v_mov_b32_e32 v108, 0
	v_mov_b32_e32 v109, 0
	v_mov_b32_e32 v110, 0
	v_mov_b32_e32 v111, 0
	v_mov_b32_e32 v112, 0
	v_mov_b32_e32 v113, 0
	v_mov_b32_e32 v114, 0
	v_mov_b32_e32 v115, 0
	v_mov_b32_e32 v116, 0
	v_mov_b32_e32 v117, 0
	v_mov_b32_e32 v118, 0
	v_mov_b32_e32 v119, 0
	v_mov_b32_e32 v120, 0
	v_mov_b32_e32 v121, 0
	v_mov_b32_e32 v122, 0
	v_mov_b32_e32 v123, 0
	v_mov_b32_e32 v124, 0
	v_mov_b32_e32 v125, 0
	v_mov_b32_e32 v126, 0
	v_mov_b32_e32 v127, 0
	v_mov_b32_e32 v199, 0
	v_mov_b32_e32 v198, 0
	v_mov_b32_e32 v171, 0
	v_mov_b32_e32 v164, 0
	v_mov_b32_e32 v140, 0
	v_mov_b32_e32 v141, 0
	v_mov_b32_e32 v142, 0
	v_mov_b32_e32 v143, 0
	v_mov_b32_e32 v144, 0
	v_mov_b32_e32 v145, 0
	v_mov_b32_e32 v146, 0
	v_mov_b32_e32 v147, 0
	v_mov_b32_e32 v148, 0
	v_mov_b32_e32 v149, 0
	v_mov_b32_e32 v150, 0
	v_mov_b32_e32 v151, 0
	v_mov_b32_e32 v152, 0
	v_mov_b32_e32 v153, 0
	v_mov_b32_e32 v154, 0
	v_mov_b32_e32 v155, 0
	s_waitcnt vmcnt(8)
	s_mov_b32 s1, 0
	s_add_i32 s0, s68, 3
	s_barrier
	ds_read_b128 v[160:163], v194
	ds_read_b128 v[176:179], v194 offset:2048
	ds_read_b128 v[180:183], v194 offset:4096
	ds_read_b128 v[204:207], v195
	ds_read_b128 v[222:225], v195 offset:2048
	ds_read_b128 v[226:229], v195 offset:4096
	ds_read_b128 v[230:233], v195 offset:6144
	ds_read_b128 v[234:237], v195 offset:8192
	ds_read_b128 v[238:241], v195 offset:10240
	ds_read_b128 v[242:245], v195 offset:12288
	ds_read_b128 v[246:249], v195 offset:14336
	ds_read_b128 v[200:203], v194 offset:6144
	s_cmp_ge_u32 s8, 0x4000
	s_cbranch_scc1 .Lgemm_disp_late
	s_cmp_eq_u32 s9, 0
	s_cbranch_scc1 .Lgemm_kloop_n
	s_cmp_eq_u32 s9, 2
	s_cbranch_scc1 .Lgemm_kloop_r1e
	s_branch .LBB0_112

; DI void epi_slab(const GemmCfg c, const f32x16 (&acc)[4], float* sW, const float* rss, const size_t row0, const int g, const int lane,
;                  float* const g_h, u16* const g_hb, float* const g_out, const int final_out) {
;     ...
;   if (c.epi == EPI_SWIGLU) {
;     const int c4 = (ln_ & 15) * 4;
; #pragma unroll 2
;     for (int it = 0; it < 8; ++it) {
;       const int r = (ln_ >> 4) + 4 * it;
;       const float rs = rsqrtf(rss[r] * invK + 1e-6f);
;       f32x4 a = *(const f32x4*)(sW + r * 132 + c4);
;       f32x4 b = *(const f32x4*)(sW + r * 132 + 64 + c4);
;       float y[4];
; #pragma unroll
;       for (int e = 0; e < 4; ++e) { float av = a[e] * rs, bv = b[e] * rs; y[e] = av * __builtin_amdgcn_rcpf(1.f + __expf(-av)) * bv; }
;       *(u32x2*)(c.o16 + (row0 + r) * DFF + g * 64 + c4) = MK2(pack2(y[0], y[1]), pack2(y[2], y[3]));
;     }
; DI void gemm_run(const GemmCfg c, char* smem, float* const g_h, u16* const g_hb, float* const g_out, const int final_out) {
;     ...
;   for (int slot = Lb; slot < ntiles; slot += G) {
;     const int sr = slot / srow, idx = slot - sr * srow;
;     const int tm = sr < 8 ? sr * 8 + (idx & 7) : 64;
;     const int tn = sr < 8 ? (idx >> 3) : idx;
;     const u16* Ag = c.A + (size_t)(tm * 256 + lrow) * c.lda + tn * c.a_koff_tn + lch * 8;
;     const u16* Bg = c.Bt + (size_t)(tn * 256 + lrow) * K + lch * 8;
.Lswg2:
	v_and_b32_e32 v222, 15, v185
	v_lshrrev_b32_e32 v223, 4, v185
	s_lshl_b32 s4, s86, 2
	s_add_i32 s4, s4, 0x24000
	v_lshl_add_u32 v224, v223, 4, s4
	ds_read_b128 v[226:229], v224
	ds_read_b128 v[230:233], v224 offset:64
	ds_read_b128 v[234:237], v224 offset:128
	ds_read_b128 v[238:241], v224 offset:192
	s_lshr_b32 s4, s86, 5
	s_or_b32 s4, s4, s75
	s_and_b32 s5, s4, 3
	s_mul_i32 s5, s5, 0x2400
	s_cmp_lt_u32 s4, 4
	s_mov_b32 s4, 0x1b000
	s_cselect_b32 s4, 0x9000, s4
	s_add_i32 s4, s4, s5
	v_mul_u32_u24_e32 v198, 0x440, v223
	v_lshl_add_u32 v198, v222, 2, v198
	v_add_u32_e32 v198, s4, v198
	v_add_u32_e32 v199, 0x1100, v198
	v_mul_u32_u24_e32 v200, 0x110, v223
	v_lshl_add_u32 v200, v222, 4, v200
	v_add_u32_e32 v200, s4, v200
	v_readlane_b32 s6, v255, 23
	v_readlane_b32 s7, v255, 24
	v_readlane_b32 s5, v255, 25
	s_lshl_b32 s1, s49, 7
	s_nop 0
	s_or_b32 s5, s5, s1
	s_lshl_b32 s5, s5, 1
	s_mul_i32 s1, s78, 0x160000
	s_add_i32 s5, s5, s1
	s_add_u32 s6, s6, s5
	s_addc_u32 s7, s7, 0
	v_mul_u32_u24_e32 v202, 0x1600, v223
	v_lshl_add_u32 v202, v222, 3, v202
	v_mov_b32_e32 v203, 0
	v_lshl_add_u64 v[202:203], v[202:203], 0, s[6:7]
	v_readlane_b32 s6, v254, 26
	s_mov_b32 s9, 0
	s_nop 0
	s_add_i32 s7, s48, s6
	s_cmp_ge_i32 s7, s74
	s_cbranch_scc1 .Lswg2_nopf
	s_abs_i32 s1, s7
	s_mul_hi_u32 s4, s1, s69
	s_mul_i32 s5, s4, s30
	s_ashr_i32 s0, s7, 31
	s_sub_i32 s1, s1, s5
	s_xor_b32 s0, s0, s63
	s_add_i32 s5, s4, 1
	s_sub_i32 s6, s1, s30
	s_cmp_ge_u32 s1, s30
	s_cselect_b32 s4, s5, s4
	s_cselect_b32 s1, s6, s1
	s_add_i32 s5, s4, 1
	s_cmp_ge_u32 s1, s30
	s_cselect_b32 s1, s5, s4
	s_xor_b32 s1, s1, s0
	s_sub_i32 s0, s1, s0
	s_mul_i32 s1, s0, s65
	s_sub_i32 s1, s7, s1
	s_lshl_b32 s4, s0, 3
	s_and_b32 s5, s7, 7
	s_or_b32 s4, s4, s5
	s_ashr_i32 s5, s1, 3
	s_cmp_lt_i32 s0, 8
	s_cselect_b32 s78, s4, 64
	s_cselect_b32 s49, s5, s1
	v_lshrrev_b32_e32 v128, 3, v185
	v_and_b32_e32 v129, 7, v185
	v_xor_b32_e32 v129, v129, v128
	v_lshlrev_b32_e32 v129, 4, v129
	s_lshl_b32 s0, s62, 1
	v_mul_lo_u32 v130, v128, s0
	s_lshl_b32 s1, s62, 4
	v_add_u32_e32 v130, v130, v129
	v_add_u32_e32 v131, s1, v130
	v_add_u32_e32 v132, s1, v131
	v_add_u32_e32 v133, s1, v132
	s_lshl_b32 s0, s60, 1
	v_mul_lo_u32 v134, v128, s0
	s_lshl_b32 s1, s60, 4
	v_add_u32_e32 v134, v134, v129
	v_add_u32_e32 v135, s1, v134
	v_add_u32_e32 v136, s1, v135
	v_add_u32_e32 v137, s1, v136
	s_lshl_b32 s8, s75, 5
	s_add_i32 s8, s8, s86
	s_lshl_b32 s0, s78, 8
	s_add_i32 s0, s0, s8
	s_mul_i32 s0, s0, s62
	s_mul_i32 s1, s49, s2
	s_add_i32 s0, s0, s1
	s_lshl_b32 s0, s0, 1
	s_add_u32 s4, s54, s0
	s_addc_u32 s5, s55, 0
	v_readlane_b32 s6, v255, 5
	v_readlane_b32 s7, v255, 6
	s_lshl_b32 s0, s49, 8
	s_add_i32 s0, s0, s8
	s_mul_i32 s0, s0, s60
	s_lshl_b32 s0, s0, 1
	s_add_u32 s6, s6, s0
	s_addc_u32 s7, s7, 0
	s_lshl_b32 s8, s8, 7
	s_add_u32 m0, s8, 0x0
	s_nop 0
	global_load_lds_dwordx4 v130, s[4:5]
	s_add_u32 m0, s8, 0x12000
	s_nop 0
	global_load_lds_dwordx4 v134, s[6:7]
	s_add_u32 m0, s8, 0x400
	s_nop 0
	global_load_lds_dwordx4 v131, s[4:5]
	s_add_u32 m0, s8, 0x12400
	s_nop 0
	global_load_lds_dwordx4 v135, s[6:7]
	s_add_u32 m0, s8, 0x800
	s_nop 0
	global_load_lds_dwordx4 v132, s[4:5]
	s_add_u32 m0, s8, 0x12800
	s_nop 0
	global_load_lds_dwordx4 v136, s[6:7]
	s_add_u32 m0, s8, 0xc00
	s_nop 0
	global_load_lds_dwordx4 v133, s[4:5]
	s_add_u32 m0, s8, 0x12c00
	s_nop 0
	global_load_lds_dwordx4 v137, s[6:7]
	s_mov_b32 s9, 1
.Lswg2_nopf:
	s_nop 0
	v_writelane_b32 v255, s9, 51
	s_mov_b64 s[8:9], 0
	s_waitcnt lgkmcnt(0)
	v_fmaak_f32 v226, v191, v226, 0x358637bd
	v_fmaak_f32 v227, v191, v227, 0x358637bd
	v_cmp_gt_f32_e32 vcc, s33, v226
	v_cmp_gt_f32_e64 s[14:15], s33, v227
	v_mul_f32_e32 v246, 0x4b800000, v226
	v_mul_f32_e32 v247, 0x4b800000, v227
	v_cndmask_b32_e32 v226, v226, v246, vcc
	v_cndmask_b32_e64 v227, v227, v247, s[14:15]
	v_rsq_f32_e32 v226, v226
	v_rsq_f32_e32 v227, v227
	s_nop 0
	v_mul_f32_e32 v246, 0x45800000, v226
	v_mul_f32_e32 v247, 0x45800000, v227
	v_cndmask_b32_e32 v226, v226, v246, vcc
	v_cndmask_b32_e64 v227, v227, v247, s[14:15]
	v_fmaak_f32 v228, v191, v228, 0x358637bd
	v_fmaak_f32 v229, v191, v229, 0x358637bd
	v_cmp_gt_f32_e32 vcc, s33, v228
	v_cmp_gt_f32_e64 s[14:15], s33, v229
	v_mul_f32_e32 v246, 0x4b800000, v228
	v_mul_f32_e32 v247, 0x4b800000, v229
	v_cndmask_b32_e32 v228, v228, v246, vcc
	v_cndmask_b32_e64 v229, v229, v247, s[14:15]
	v_rsq_f32_e32 v228, v228
	v_rsq_f32_e32 v229, v229
	s_nop 0
	v_mul_f32_e32 v246, 0x45800000, v228
	v_mul_f32_e32 v247, 0x45800000, v229
	v_cndmask_b32_e32 v228, v228, v246, vcc
	v_cndmask_b32_e64 v229, v229, v247, s[14:15]
	v_fmaak_f32 v230, v191, v230, 0x358637bd
	v_fmaak_f32 v231, v191, v231, 0x358637bd
	v_cmp_gt_f32_e32 vcc, s33, v230
	v_cmp_gt_f32_e64 s[14:15], s33, v231
	v_mul_f32_e32 v246, 0x4b800000, v230
	v_mul_f32_e32 v247, 0x4b800000, v231
	v_cndmask_b32_e32 v230, v230, v246, vcc
	v_cndmask_b32_e64 v231, v231, v247, s[14:15]
	v_rsq_f32_e32 v230, v230
	v_rsq_f32_e32 v231, v231
	s_nop 0
	v_mul_f32_e32 v246, 0x45800000, v230
	v_mul_f32_e32 v247, 0x45800000, v231
	v_cndmask_b32_e32 v230, v230, v246, vcc
	v_cndmask_b32_e64 v231, v231, v247, s[14:15]
	v_fmaak_f32 v232, v191, v232, 0x358637bd
	v_fmaak_f32 v233, v191, v233, 0x358637bd
	v_cmp_gt_f32_e32 vcc, s33, v232
	v_cmp_gt_f32_e64 s[14:15], s33, v233
	v_mul_f32_e32 v246, 0x4b800000, v232
	v_mul_f32_e32 v247, 0x4b800000, v233
	v_cndmask_b32_e32 v232, v232, v246, vcc
	v_cndmask_b32_e64 v233, v233, v247, s[14:15]
	v_rsq_f32_e32 v232, v232
	v_rsq_f32_e32 v233, v233
	s_nop 0
	v_mul_f32_e32 v246, 0x45800000, v232
	v_mul_f32_e32 v247, 0x45800000, v233
	v_cndmask_b32_e32 v232, v232, v246, vcc
; DI void epi_slab(const GemmCfg c, const f32x16 (&acc)[4], float* sW, const float* rss, const size_t row0, const int g, const int lane,
;                  float* const g_h, u16* const g_hb, float* const g_out, const int final_out) {
;     ...
;   if (c.epi == EPI_SWIGLU) {
;     const int c4 = (ln_ & 15) * 4;
; #pragma unroll 2
;     for (int it = 0; it < 8; ++it) {
;       const int r = (ln_ >> 4) + 4 * it;
;       const float rs = rsqrtf(rss[r] * invK + 1e-6f);
;       f32x4 a = *(const f32x4*)(sW + r * 132 + c4);
;       f32x4 b = *(const f32x4*)(sW + r * 132 + 64 + c4);
;       float y[4];
; #pragma unroll
;       for (int e = 0; e < 4; ++e) { float av = a[e] * rs, bv = b[e] * rs; y[e] = av * __builtin_amdgcn_rcpf(1.f + __expf(-av)) * bv; }
;       *(u32x2*)(c.o16 + (row0 + r) * DFF + g * 64 + c4) = MK2(pack2(y[0], y[1]), pack2(y[2], y[3]));
;     }
	v_cndmask_b32_e64 v233, v233, v247, s[14:15]
	v_fmaak_f32 v234, v191, v234, 0x358637bd
	v_fmaak_f32 v235, v191, v235, 0x358637bd
	v_cmp_gt_f32_e32 vcc, s33, v234
	v_cmp_gt_f32_e64 s[14:15], s33, v235
	v_mul_f32_e32 v246, 0x4b800000, v234
	v_mul_f32_e32 v247, 0x4b800000, v235
	v_cndmask_b32_e32 v234, v234, v246, vcc
	v_cndmask_b32_e64 v235, v235, v247, s[14:15]
	v_rsq_f32_e32 v234, v234
	v_rsq_f32_e32 v235, v235
	s_nop 0
	v_mul_f32_e32 v246, 0x45800000, v234
	v_mul_f32_e32 v247, 0x45800000, v235
	v_cndmask_b32_e32 v234, v234, v246, vcc
	v_cndmask_b32_e64 v235, v235, v247, s[14:15]
	v_fmaak_f32 v236, v191, v236, 0x358637bd
	v_fmaak_f32 v237, v191, v237, 0x358637bd
	v_cmp_gt_f32_e32 vcc, s33, v236
	v_cmp_gt_f32_e64 s[14:15], s33, v237
	v_mul_f32_e32 v246, 0x4b800000, v236
	v_mul_f32_e32 v247, 0x4b800000, v237
	v_cndmask_b32_e32 v236, v236, v246, vcc
	v_cndmask_b32_e64 v237, v237, v247, s[14:15]
	v_rsq_f32_e32 v236, v236
	v_rsq_f32_e32 v237, v237
	s_nop 0
	v_mul_f32_e32 v246, 0x45800000, v236
	v_mul_f32_e32 v247, 0x45800000, v237
	v_cndmask_b32_e32 v236, v236, v246, vcc
	v_cndmask_b32_e64 v237, v237, v247, s[14:15]
	v_fmaak_f32 v238, v191, v238, 0x358637bd
	v_fmaak_f32 v239, v191, v239, 0x358637bd
	v_cmp_gt_f32_e32 vcc, s33, v238
	v_cmp_gt_f32_e64 s[14:15], s33, v239
	v_mul_f32_e32 v246, 0x4b800000, v238
	v_mul_f32_e32 v247, 0x4b800000, v239
	v_cndmask_b32_e32 v238, v238, v246, vcc
	v_cndmask_b32_e64 v239, v239, v247, s[14:15]
	v_rsq_f32_e32 v238, v238
	v_rsq_f32_e32 v239, v239
	s_nop 0
	v_mul_f32_e32 v246, 0x45800000, v238
	v_mul_f32_e32 v247, 0x45800000, v239
	v_cndmask_b32_e32 v238, v238, v246, vcc
	v_cndmask_b32_e64 v239, v239, v247, s[14:15]
	v_fmaak_f32 v240, v191, v240, 0x358637bd
	v_fmaak_f32 v241, v191, v241, 0x358637bd
	v_cmp_gt_f32_e32 vcc, s33, v240
	v_cmp_gt_f32_e64 s[14:15], s33, v241
	v_mul_f32_e32 v246, 0x4b800000, v240
	v_mul_f32_e32 v247, 0x4b800000, v241
	v_cndmask_b32_e32 v240, v240, v246, vcc
	v_cndmask_b32_e64 v241, v241, v247, s[14:15]
	v_rsq_f32_e32 v240, v240
	v_rsq_f32_e32 v241, v241
	s_nop 0
	v_mul_f32_e32 v246, 0x45800000, v240
	v_mul_f32_e32 v247, 0x45800000, v241
	v_cndmask_b32_e32 v240, v240, v246, vcc
	v_cndmask_b32_e64 v241, v241, v247, s[14:15]
	v_pk_mul_f32 v[64:65], v[64:65], v[226:227]
	v_pk_mul_f32 v[66:67], v[66:67], v[228:229]
	v_pk_mul_f32 v[80:81], v[80:81], v[226:227]
	v_pk_mul_f32 v[82:83], v[82:83], v[228:229]
	v_mul_f32_e32 v242, 0xbfb8aa3b, v64
	v_mul_f32_e32 v243, 0xbfb8aa3b, v65
	v_mul_f32_e32 v244, 0xbfb8aa3b, v66
	v_mul_f32_e32 v245, 0xbfb8aa3b, v67
	v_exp_f32_e32 v242, v242
	v_exp_f32_e32 v243, v243
	v_exp_f32_e32 v244, v244
	v_exp_f32_e32 v245, v245
	v_add_f32_e32 v242, 1.0, v242
	v_add_f32_e32 v243, 1.0, v243
	v_add_f32_e32 v244, 1.0, v244
	v_add_f32_e32 v245, 1.0, v245
	v_rcp_f32_e32 v242, v242
	v_rcp_f32_e32 v243, v243
	v_rcp_f32_e32 v244, v244
	v_rcp_f32_e32 v245, v245
	s_nop 0
	v_pk_mul_f32 v[64:65], v[64:65], v[242:243]
	v_pk_mul_f32 v[66:67], v[66:67], v[244:245]
	v_pk_mul_f32 v[64:65], v[80:81], v[64:65]
	v_pk_mul_f32 v[66:67], v[82:83], v[66:67]
	ds_write2_b32 v198, v64, v65 offset0:0 offset1:68
	ds_write2_b32 v198, v66, v67 offset0:136 offset1:204
	v_pk_mul_f32 v[68:69], v[68:69], v[226:227]
	v_pk_mul_f32 v[70:71], v[70:71], v[228:229]
	v_pk_mul_f32 v[84:85], v[84:85], v[226:227]
	v_pk_mul_f32 v[86:87], v[86:87], v[228:229]
	v_mul_f32_e32 v242, 0xbfb8aa3b, v68
	v_mul_f32_e32 v243, 0xbfb8aa3b, v69
	v_mul_f32_e32 v244, 0xbfb8aa3b, v70
	v_mul_f32_e32 v245, 0xbfb8aa3b, v71
	v_exp_f32_e32 v242, v242
	v_exp_f32_e32 v243, v243
	v_exp_f32_e32 v244, v244
	v_exp_f32_e32 v245, v245
	v_add_f32_e32 v242, 1.0, v242
	v_add_f32_e32 v243, 1.0, v243
	v_add_f32_e32 v244, 1.0, v244
	v_add_f32_e32 v245, 1.0, v245
	v_rcp_f32_e32 v242, v242
	v_rcp_f32_e32 v243, v243
	v_rcp_f32_e32 v244, v244
	v_rcp_f32_e32 v245, v245
	s_nop 0
	v_pk_mul_f32 v[68:69], v[68:69], v[242:243]
	v_pk_mul_f32 v[70:71], v[70:71], v[244:245]
	v_pk_mul_f32 v[68:69], v[84:85], v[68:69]
	v_pk_mul_f32 v[70:71], v[86:87], v[70:71]
	ds_write2_b32 v198, v68, v69 offset0:16 offset1:84
	ds_write2_b32 v198, v70, v71 offset0:152 offset1:220
	v_pk_mul_f32 v[72:73], v[72:73], v[226:227]
	v_pk_mul_f32 v[74:75], v[74:75], v[228:229]
	v_pk_mul_f32 v[88:89], v[88:89], v[226:227]
	v_pk_mul_f32 v[90:91], v[90:91], v[228:229]
	v_mul_f32_e32 v242, 0xbfb8aa3b, v72
	v_mul_f32_e32 v243, 0xbfb8aa3b, v73
	v_mul_f32_e32 v244, 0xbfb8aa3b, v74
	v_mul_f32_e32 v245, 0xbfb8aa3b, v75
	v_exp_f32_e32 v242, v242
	v_exp_f32_e32 v243, v243
	v_exp_f32_e32 v244, v244
	v_exp_f32_e32 v245, v245
	v_add_f32_e32 v242, 1.0, v242
	v_add_f32_e32 v243, 1.0, v243
	v_add_f32_e32 v244, 1.0, v244
	v_add_f32_e32 v245, 1.0, v245
	v_rcp_f32_e32 v242, v242
	v_rcp_f32_e32 v243, v243
	v_rcp_f32_e32 v244, v244
	v_rcp_f32_e32 v245, v245
	s_nop 0
	v_pk_mul_f32 v[72:73], v[72:73], v[242:243]
	v_pk_mul_f32 v[74:75], v[74:75], v[244:245]
	v_pk_mul_f32 v[72:73], v[88:89], v[72:73]
	v_pk_mul_f32 v[74:75], v[90:91], v[74:75]
	ds_write2_b32 v198, v72, v73 offset0:32 offset1:100
	ds_write2_b32 v198, v74, v75 offset0:168 offset1:236
	v_pk_mul_f32 v[76:77], v[76:77], v[226:227]
	v_pk_mul_f32 v[78:79], v[78:79], v[228:229]
	v_pk_mul_f32 v[92:93], v[92:93], v[226:227]
	v_pk_mul_f32 v[94:95], v[94:95], v[228:229]
	v_mul_f32_e32 v242, 0xbfb8aa3b, v76
	v_mul_f32_e32 v243, 0xbfb8aa3b, v77
	v_mul_f32_e32 v244, 0xbfb8aa3b, v78
	v_mul_f32_e32 v245, 0xbfb8aa3b, v79
	v_exp_f32_e32 v242, v242
	v_exp_f32_e32 v243, v243
	v_exp_f32_e32 v244, v244
	v_exp_f32_e32 v245, v245
	v_add_f32_e32 v242, 1.0, v242
	v_add_f32_e32 v243, 1.0, v243
	v_add_f32_e32 v244, 1.0, v244
	v_add_f32_e32 v245, 1.0, v245
	v_rcp_f32_e32 v242, v242
; DI void epi_slab(const GemmCfg c, const f32x16 (&acc)[4], float* sW, const float* rss, const size_t row0, const int g, const int lane,
;                  float* const g_h, u16* const g_hb, float* const g_out, const int final_out) {
;     ...
;   if (c.epi == EPI_SWIGLU) {
;     const int c4 = (ln_ & 15) * 4;
; #pragma unroll 2
;     for (int it = 0; it < 8; ++it) {
;       const int r = (ln_ >> 4) + 4 * it;
;       const float rs = rsqrtf(rss[r] * invK + 1e-6f);
;       f32x4 a = *(const f32x4*)(sW + r * 132 + c4);
;       f32x4 b = *(const f32x4*)(sW + r * 132 + 64 + c4);
;       float y[4];
; #pragma unroll
;       for (int e = 0; e < 4; ++e) { float av = a[e] * rs, bv = b[e] * rs; y[e] = av * __builtin_amdgcn_rcpf(1.f + __expf(-av)) * bv; }
;       *(u32x2*)(c.o16 + (row0 + r) * DFF + g * 64 + c4) = MK2(pack2(y[0], y[1]), pack2(y[2], y[3]));
;     }
	v_rcp_f32_e32 v243, v243
	v_rcp_f32_e32 v244, v244
	v_rcp_f32_e32 v245, v245
	s_nop 0
	v_pk_mul_f32 v[76:77], v[76:77], v[242:243]
	v_pk_mul_f32 v[78:79], v[78:79], v[244:245]
	v_pk_mul_f32 v[76:77], v[92:93], v[76:77]
	v_pk_mul_f32 v[78:79], v[94:95], v[78:79]
	ds_write2_b32 v198, v76, v77 offset0:48 offset1:116
	ds_write2_b32 v198, v78, v79 offset0:184 offset1:252
	v_pk_mul_f32 v[96:97], v[96:97], v[230:231]
	v_pk_mul_f32 v[98:99], v[98:99], v[232:233]
	v_pk_mul_f32 v[112:113], v[112:113], v[230:231]
	v_pk_mul_f32 v[114:115], v[114:115], v[232:233]
	v_mul_f32_e32 v242, 0xbfb8aa3b, v96
	v_mul_f32_e32 v243, 0xbfb8aa3b, v97
	v_mul_f32_e32 v244, 0xbfb8aa3b, v98
	v_mul_f32_e32 v245, 0xbfb8aa3b, v99
	v_exp_f32_e32 v242, v242
	v_exp_f32_e32 v243, v243
	v_exp_f32_e32 v244, v244
	v_exp_f32_e32 v245, v245
	v_add_f32_e32 v242, 1.0, v242
	v_add_f32_e32 v243, 1.0, v243
	v_add_f32_e32 v244, 1.0, v244
	v_add_f32_e32 v245, 1.0, v245
	v_rcp_f32_e32 v242, v242
	v_rcp_f32_e32 v243, v243
	v_rcp_f32_e32 v244, v244
	v_rcp_f32_e32 v245, v245
	s_nop 0
	v_pk_mul_f32 v[96:97], v[96:97], v[242:243]
	v_pk_mul_f32 v[98:99], v[98:99], v[244:245]
	v_pk_mul_f32 v[96:97], v[112:113], v[96:97]
	v_pk_mul_f32 v[98:99], v[114:115], v[98:99]
	ds_write2_b32 v199, v96, v97 offset0:0 offset1:68
	ds_write2_b32 v199, v98, v99 offset0:136 offset1:204
	v_pk_mul_f32 v[100:101], v[100:101], v[230:231]
	v_pk_mul_f32 v[102:103], v[102:103], v[232:233]
	v_pk_mul_f32 v[116:117], v[116:117], v[230:231]
	v_pk_mul_f32 v[118:119], v[118:119], v[232:233]
	v_mul_f32_e32 v242, 0xbfb8aa3b, v100
	v_mul_f32_e32 v243, 0xbfb8aa3b, v101
	v_mul_f32_e32 v244, 0xbfb8aa3b, v102
	v_mul_f32_e32 v245, 0xbfb8aa3b, v103
	v_exp_f32_e32 v242, v242
	v_exp_f32_e32 v243, v243
	v_exp_f32_e32 v244, v244
	v_exp_f32_e32 v245, v245
	v_add_f32_e32 v242, 1.0, v242
	v_add_f32_e32 v243, 1.0, v243
	v_add_f32_e32 v244, 1.0, v244
	v_add_f32_e32 v245, 1.0, v245
	v_rcp_f32_e32 v242, v242
	v_rcp_f32_e32 v243, v243
	v_rcp_f32_e32 v244, v244
	v_rcp_f32_e32 v245, v245
	s_nop 0
	v_pk_mul_f32 v[100:101], v[100:101], v[242:243]
	v_pk_mul_f32 v[102:103], v[102:103], v[244:245]
	v_pk_mul_f32 v[100:101], v[116:117], v[100:101]
	v_pk_mul_f32 v[102:103], v[118:119], v[102:103]
	ds_write2_b32 v199, v100, v101 offset0:16 offset1:84
	ds_write2_b32 v199, v102, v103 offset0:152 offset1:220
	v_pk_mul_f32 v[104:105], v[104:105], v[230:231]
	v_pk_mul_f32 v[106:107], v[106:107], v[232:233]
	v_pk_mul_f32 v[120:121], v[120:121], v[230:231]
	v_pk_mul_f32 v[122:123], v[122:123], v[232:233]
	v_mul_f32_e32 v242, 0xbfb8aa3b, v104
	v_mul_f32_e32 v243, 0xbfb8aa3b, v105
	v_mul_f32_e32 v244, 0xbfb8aa3b, v106
	v_mul_f32_e32 v245, 0xbfb8aa3b, v107
	v_exp_f32_e32 v242, v242
	v_exp_f32_e32 v243, v243
	v_exp_f32_e32 v244, v244
	v_exp_f32_e32 v245, v245
	v_add_f32_e32 v242, 1.0, v242
	v_add_f32_e32 v243, 1.0, v243
	v_add_f32_e32 v244, 1.0, v244
	v_add_f32_e32 v245, 1.0, v245
	v_rcp_f32_e32 v242, v242
	v_rcp_f32_e32 v243, v243
	v_rcp_f32_e32 v244, v244
	v_rcp_f32_e32 v245, v245
	s_nop 0
	v_pk_mul_f32 v[104:105], v[104:105], v[242:243]
	v_pk_mul_f32 v[106:107], v[106:107], v[244:245]
	v_pk_mul_f32 v[104:105], v[120:121], v[104:105]
	v_pk_mul_f32 v[106:107], v[122:123], v[106:107]
	ds_write2_b32 v199, v104, v105 offset0:32 offset1:100
	ds_write2_b32 v199, v106, v107 offset0:168 offset1:236
	v_pk_mul_f32 v[108:109], v[108:109], v[230:231]
	v_pk_mul_f32 v[110:111], v[110:111], v[232:233]
	v_pk_mul_f32 v[124:125], v[124:125], v[230:231]
	v_pk_mul_f32 v[126:127], v[126:127], v[232:233]
	v_mul_f32_e32 v242, 0xbfb8aa3b, v108
	v_mul_f32_e32 v243, 0xbfb8aa3b, v109
	v_mul_f32_e32 v244, 0xbfb8aa3b, v110
	v_mul_f32_e32 v245, 0xbfb8aa3b, v111
	v_exp_f32_e32 v242, v242
	v_exp_f32_e32 v243, v243
	v_exp_f32_e32 v244, v244
	v_exp_f32_e32 v245, v245
	v_add_f32_e32 v242, 1.0, v242
	v_add_f32_e32 v243, 1.0, v243
	v_add_f32_e32 v244, 1.0, v244
	v_add_f32_e32 v245, 1.0, v245
	v_rcp_f32_e32 v242, v242
	v_rcp_f32_e32 v243, v243
	v_rcp_f32_e32 v244, v244
	v_rcp_f32_e32 v245, v245
	s_nop 0
	v_pk_mul_f32 v[108:109], v[108:109], v[242:243]
	v_pk_mul_f32 v[110:111], v[110:111], v[244:245]
	v_pk_mul_f32 v[108:109], v[124:125], v[108:109]
	v_pk_mul_f32 v[110:111], v[126:127], v[110:111]
	ds_write2_b32 v199, v108, v109 offset0:48 offset1:116
	ds_write2_b32 v199, v110, v111 offset0:184 offset1:252
	s_waitcnt lgkmcnt(0)
	ds_read_b128 v[80:83], v200
	ds_read_b128 v[84:87], v200 offset:1088
	ds_read_b128 v[88:91], v200 offset:2176
	ds_read_b128 v[92:95], v200 offset:3264
	ds_read_b128 v[112:115], v200 offset:4352
	ds_read_b128 v[116:119], v200 offset:5440
	ds_read_b128 v[120:123], v200 offset:6528
	ds_read_b128 v[124:127], v200 offset:7616
	s_waitcnt lgkmcnt(7)
	v_lshl_add_u64 v[204:205], v[202:203], 0, s[8:9]
	v_cvt_pk_bf16_f32 v80, v80, v81
	v_cvt_pk_bf16_f32 v81, v82, v83
	s_add_u32 s8, s8, 0x5800
	s_addc_u32 s9, s9, 0
	global_store_dwordx2 v[204:205], v[80:81], off
	s_waitcnt lgkmcnt(6)
	v_lshl_add_u64 v[204:205], v[202:203], 0, s[8:9]
	v_cvt_pk_bf16_f32 v84, v84, v85
	v_cvt_pk_bf16_f32 v85, v86, v87
	s_add_u32 s8, s8, 0x5800
	s_addc_u32 s9, s9, 0
	global_store_dwordx2 v[204:205], v[84:85], off
	s_waitcnt lgkmcnt(5)
	v_lshl_add_u64 v[204:205], v[202:203], 0, s[8:9]
	v_cvt_pk_bf16_f32 v88, v88, v89
	v_cvt_pk_bf16_f32 v89, v90, v91
	s_add_u32 s8, s8, 0x5800
	s_addc_u32 s9, s9, 0
	global_store_dwordx2 v[204:205], v[88:89], off
	s_waitcnt lgkmcnt(4)
	v_lshl_add_u64 v[204:205], v[202:203], 0, s[8:9]
	v_cvt_pk_bf16_f32 v92, v92, v93
	v_cvt_pk_bf16_f32 v93, v94, v95
	s_add_u32 s8, s8, 0x5800
	s_addc_u32 s9, s9, 0
	global_store_dwordx2 v[204:205], v[92:93], off
	s_waitcnt lgkmcnt(3)
; DI void epi_slab(const GemmCfg c, const f32x16 (&acc)[4], float* sW, const float* rss, const size_t row0, const int g, const int lane,
;                  float* const g_h, u16* const g_hb, float* const g_out, const int final_out) {
;     ...
;   if (c.epi == EPI_SWIGLU) {
;     const int c4 = (ln_ & 15) * 4;
; #pragma unroll 2
;     for (int it = 0; it < 8; ++it) {
;       const int r = (ln_ >> 4) + 4 * it;
;       const float rs = rsqrtf(rss[r] * invK + 1e-6f);
;       f32x4 a = *(const f32x4*)(sW + r * 132 + c4);
;       f32x4 b = *(const f32x4*)(sW + r * 132 + 64 + c4);
;       float y[4];
; #pragma unroll
;       for (int e = 0; e < 4; ++e) { float av = a[e] * rs, bv = b[e] * rs; y[e] = av * __builtin_amdgcn_rcpf(1.f + __expf(-av)) * bv; }
;       *(u32x2*)(c.o16 + (row0 + r) * DFF + g * 64 + c4) = MK2(pack2(y[0], y[1]), pack2(y[2], y[3]));
;     }
	v_lshl_add_u64 v[204:205], v[202:203], 0, s[8:9]
	v_cvt_pk_bf16_f32 v112, v112, v113
	v_cvt_pk_bf16_f32 v113, v114, v115
	s_add_u32 s8, s8, 0x5800
	s_addc_u32 s9, s9, 0
	global_store_dwordx2 v[204:205], v[112:113], off
	s_waitcnt lgkmcnt(2)
	v_lshl_add_u64 v[204:205], v[202:203], 0, s[8:9]
	v_cvt_pk_bf16_f32 v116, v116, v117
	v_cvt_pk_bf16_f32 v117, v118, v119
	s_add_u32 s8, s8, 0x5800
	s_addc_u32 s9, s9, 0
	global_store_dwordx2 v[204:205], v[116:117], off
	s_waitcnt lgkmcnt(1)
	v_lshl_add_u64 v[204:205], v[202:203], 0, s[8:9]
	v_cvt_pk_bf16_f32 v120, v120, v121
	v_cvt_pk_bf16_f32 v121, v122, v123
	s_add_u32 s8, s8, 0x5800
	s_addc_u32 s9, s9, 0
	global_store_dwordx2 v[204:205], v[120:121], off
	s_waitcnt lgkmcnt(0)
	v_lshl_add_u64 v[204:205], v[202:203], 0, s[8:9]
	v_cvt_pk_bf16_f32 v124, v124, v125
	v_cvt_pk_bf16_f32 v125, v126, v127
	s_add_u32 s8, s8, 0x5800
	s_addc_u32 s9, s9, 0
	global_store_dwordx2 v[204:205], v[124:125], off
	v_pk_mul_f32 v[0:1], v[0:1], v[234:235]
	v_pk_mul_f32 v[2:3], v[2:3], v[236:237]
	v_pk_mul_f32 v[16:17], v[16:17], v[234:235]
	v_pk_mul_f32 v[18:19], v[18:19], v[236:237]
	v_mul_f32_e32 v242, 0xbfb8aa3b, v0
	v_mul_f32_e32 v243, 0xbfb8aa3b, v1
	v_mul_f32_e32 v244, 0xbfb8aa3b, v2
	v_mul_f32_e32 v245, 0xbfb8aa3b, v3
	v_exp_f32_e32 v242, v242
	v_exp_f32_e32 v243, v243
	v_exp_f32_e32 v244, v244
	v_exp_f32_e32 v245, v245
	v_add_f32_e32 v242, 1.0, v242
	v_add_f32_e32 v243, 1.0, v243
	v_add_f32_e32 v244, 1.0, v244
	v_add_f32_e32 v245, 1.0, v245
	v_rcp_f32_e32 v242, v242
	v_rcp_f32_e32 v243, v243
	v_rcp_f32_e32 v244, v244
	v_rcp_f32_e32 v245, v245
	s_nop 0
	v_pk_mul_f32 v[0:1], v[0:1], v[242:243]
	v_pk_mul_f32 v[2:3], v[2:3], v[244:245]
	v_pk_mul_f32 v[0:1], v[16:17], v[0:1]
	v_pk_mul_f32 v[2:3], v[18:19], v[2:3]
	ds_write2_b32 v198, v0, v1 offset0:0 offset1:68
	ds_write2_b32 v198, v2, v3 offset0:136 offset1:204
	v_pk_mul_f32 v[4:5], v[4:5], v[234:235]
	v_pk_mul_f32 v[6:7], v[6:7], v[236:237]
	v_pk_mul_f32 v[20:21], v[20:21], v[234:235]
	v_pk_mul_f32 v[22:23], v[22:23], v[236:237]
	v_mul_f32_e32 v242, 0xbfb8aa3b, v4
	v_mul_f32_e32 v243, 0xbfb8aa3b, v5
	v_mul_f32_e32 v244, 0xbfb8aa3b, v6
	v_mul_f32_e32 v245, 0xbfb8aa3b, v7
	v_exp_f32_e32 v242, v242
	v_exp_f32_e32 v243, v243
	v_exp_f32_e32 v244, v244
	v_exp_f32_e32 v245, v245
	v_add_f32_e32 v242, 1.0, v242
	v_add_f32_e32 v243, 1.0, v243
	v_add_f32_e32 v244, 1.0, v244
	v_add_f32_e32 v245, 1.0, v245
	v_rcp_f32_e32 v242, v242
	v_rcp_f32_e32 v243, v243
	v_rcp_f32_e32 v244, v244
	v_rcp_f32_e32 v245, v245
	s_nop 0
	v_pk_mul_f32 v[4:5], v[4:5], v[242:243]
	v_pk_mul_f32 v[6:7], v[6:7], v[244:245]
	v_pk_mul_f32 v[4:5], v[20:21], v[4:5]
	v_pk_mul_f32 v[6:7], v[22:23], v[6:7]
	ds_write2_b32 v198, v4, v5 offset0:16 offset1:84
	ds_write2_b32 v198, v6, v7 offset0:152 offset1:220
	v_pk_mul_f32 v[8:9], v[8:9], v[234:235]
	v_pk_mul_f32 v[10:11], v[10:11], v[236:237]
	v_pk_mul_f32 v[24:25], v[24:25], v[234:235]
	v_pk_mul_f32 v[26:27], v[26:27], v[236:237]
	v_mul_f32_e32 v242, 0xbfb8aa3b, v8
	v_mul_f32_e32 v243, 0xbfb8aa3b, v9
	v_mul_f32_e32 v244, 0xbfb8aa3b, v10
	v_mul_f32_e32 v245, 0xbfb8aa3b, v11
	v_exp_f32_e32 v242, v242
	v_exp_f32_e32 v243, v243
	v_exp_f32_e32 v244, v244
	v_exp_f32_e32 v245, v245
	v_add_f32_e32 v242, 1.0, v242
	v_add_f32_e32 v243, 1.0, v243
	v_add_f32_e32 v244, 1.0, v244
	v_add_f32_e32 v245, 1.0, v245
	v_rcp_f32_e32 v242, v242
	v_rcp_f32_e32 v243, v243
	v_rcp_f32_e32 v244, v244
	v_rcp_f32_e32 v245, v245
	s_nop 0
	v_pk_mul_f32 v[8:9], v[8:9], v[242:243]
	v_pk_mul_f32 v[10:11], v[10:11], v[244:245]
	v_pk_mul_f32 v[8:9], v[24:25], v[8:9]
	v_pk_mul_f32 v[10:11], v[26:27], v[10:11]
	ds_write2_b32 v198, v8, v9 offset0:32 offset1:100
	ds_write2_b32 v198, v10, v11 offset0:168 offset1:236
	v_pk_mul_f32 v[12:13], v[12:13], v[234:235]
	v_pk_mul_f32 v[14:15], v[14:15], v[236:237]
	v_pk_mul_f32 v[28:29], v[28:29], v[234:235]
	v_pk_mul_f32 v[30:31], v[30:31], v[236:237]
	v_mul_f32_e32 v242, 0xbfb8aa3b, v12
	v_mul_f32_e32 v243, 0xbfb8aa3b, v13
	v_mul_f32_e32 v244, 0xbfb8aa3b, v14
	v_mul_f32_e32 v245, 0xbfb8aa3b, v15
	v_exp_f32_e32 v242, v242
	v_exp_f32_e32 v243, v243
	v_exp_f32_e32 v244, v244
	v_exp_f32_e32 v245, v245
	v_add_f32_e32 v242, 1.0, v242
	v_add_f32_e32 v243, 1.0, v243
	v_add_f32_e32 v244, 1.0, v244
	v_add_f32_e32 v245, 1.0, v245
	v_rcp_f32_e32 v242, v242
	v_rcp_f32_e32 v243, v243
	v_rcp_f32_e32 v244, v244
	v_rcp_f32_e32 v245, v245
	s_nop 0
	v_pk_mul_f32 v[12:13], v[12:13], v[242:243]
	v_pk_mul_f32 v[14:15], v[14:15], v[244:245]
	v_pk_mul_f32 v[12:13], v[28:29], v[12:13]
	v_pk_mul_f32 v[14:15], v[30:31], v[14:15]
	ds_write2_b32 v198, v12, v13 offset0:48 offset1:116
	ds_write2_b32 v198, v14, v15 offset0:184 offset1:252
	v_pk_mul_f32 v[32:33], v[32:33], v[238:239]
	v_pk_mul_f32 v[34:35], v[34:35], v[240:241]
	v_pk_mul_f32 v[48:49], v[48:49], v[238:239]
	v_pk_mul_f32 v[50:51], v[50:51], v[240:241]
	v_mul_f32_e32 v242, 0xbfb8aa3b, v32
	v_mul_f32_e32 v243, 0xbfb8aa3b, v33
	v_mul_f32_e32 v244, 0xbfb8aa3b, v34
	v_mul_f32_e32 v245, 0xbfb8aa3b, v35
	v_exp_f32_e32 v242, v242
	v_exp_f32_e32 v243, v243
	v_exp_f32_e32 v244, v244
	v_exp_f32_e32 v245, v245
	v_add_f32_e32 v242, 1.0, v242
	v_add_f32_e32 v243, 1.0, v243
	v_add_f32_e32 v244, 1.0, v244
	v_add_f32_e32 v245, 1.0, v245
	v_rcp_f32_e32 v242, v242
	v_rcp_f32_e32 v243, v243
	v_rcp_f32_e32 v244, v244
	v_rcp_f32_e32 v245, v245
	s_nop 0
; DI void epi_slab(const GemmCfg c, const f32x16 (&acc)[4], float* sW, const float* rss, const size_t row0, const int g, const int lane,
;                  float* const g_h, u16* const g_hb, float* const g_out, const int final_out) {
;     ...
;   if (c.epi == EPI_SWIGLU) {
;     const int c4 = (ln_ & 15) * 4;
; #pragma unroll 2
;     for (int it = 0; it < 8; ++it) {
;       const int r = (ln_ >> 4) + 4 * it;
;       const float rs = rsqrtf(rss[r] * invK + 1e-6f);
;       f32x4 a = *(const f32x4*)(sW + r * 132 + c4);
;       f32x4 b = *(const f32x4*)(sW + r * 132 + 64 + c4);
;       float y[4];
; #pragma unroll
;       for (int e = 0; e < 4; ++e) { float av = a[e] * rs, bv = b[e] * rs; y[e] = av * __builtin_amdgcn_rcpf(1.f + __expf(-av)) * bv; }
;       *(u32x2*)(c.o16 + (row0 + r) * DFF + g * 64 + c4) = MK2(pack2(y[0], y[1]), pack2(y[2], y[3]));
;     }
	v_pk_mul_f32 v[32:33], v[32:33], v[242:243]
	v_pk_mul_f32 v[34:35], v[34:35], v[244:245]
	v_pk_mul_f32 v[32:33], v[48:49], v[32:33]
	v_pk_mul_f32 v[34:35], v[50:51], v[34:35]
	ds_write2_b32 v199, v32, v33 offset0:0 offset1:68
	ds_write2_b32 v199, v34, v35 offset0:136 offset1:204
	v_pk_mul_f32 v[36:37], v[36:37], v[238:239]
	v_pk_mul_f32 v[38:39], v[38:39], v[240:241]
	v_pk_mul_f32 v[52:53], v[52:53], v[238:239]
	v_pk_mul_f32 v[54:55], v[54:55], v[240:241]
	v_mul_f32_e32 v242, 0xbfb8aa3b, v36
	v_mul_f32_e32 v243, 0xbfb8aa3b, v37
	v_mul_f32_e32 v244, 0xbfb8aa3b, v38
	v_mul_f32_e32 v245, 0xbfb8aa3b, v39
	v_exp_f32_e32 v242, v242
	v_exp_f32_e32 v243, v243
	v_exp_f32_e32 v244, v244
	v_exp_f32_e32 v245, v245
	v_add_f32_e32 v242, 1.0, v242
	v_add_f32_e32 v243, 1.0, v243
	v_add_f32_e32 v244, 1.0, v244
	v_add_f32_e32 v245, 1.0, v245
	v_rcp_f32_e32 v242, v242
	v_rcp_f32_e32 v243, v243
	v_rcp_f32_e32 v244, v244
	v_rcp_f32_e32 v245, v245
	s_nop 0
	v_pk_mul_f32 v[36:37], v[36:37], v[242:243]
	v_pk_mul_f32 v[38:39], v[38:39], v[244:245]
	v_pk_mul_f32 v[36:37], v[52:53], v[36:37]
	v_pk_mul_f32 v[38:39], v[54:55], v[38:39]
	ds_write2_b32 v199, v36, v37 offset0:16 offset1:84
	ds_write2_b32 v199, v38, v39 offset0:152 offset1:220
	v_pk_mul_f32 v[40:41], v[40:41], v[238:239]
	v_pk_mul_f32 v[42:43], v[42:43], v[240:241]
	v_pk_mul_f32 v[56:57], v[56:57], v[238:239]
	v_pk_mul_f32 v[58:59], v[58:59], v[240:241]
	v_mul_f32_e32 v242, 0xbfb8aa3b, v40
	v_mul_f32_e32 v243, 0xbfb8aa3b, v41
	v_mul_f32_e32 v244, 0xbfb8aa3b, v42
	v_mul_f32_e32 v245, 0xbfb8aa3b, v43
	v_exp_f32_e32 v242, v242
	v_exp_f32_e32 v243, v243
	v_exp_f32_e32 v244, v244
	v_exp_f32_e32 v245, v245
	v_add_f32_e32 v242, 1.0, v242
	v_add_f32_e32 v243, 1.0, v243
	v_add_f32_e32 v244, 1.0, v244
	v_add_f32_e32 v245, 1.0, v245
	v_rcp_f32_e32 v242, v242
	v_rcp_f32_e32 v243, v243
	v_rcp_f32_e32 v244, v244
	v_rcp_f32_e32 v245, v245
	s_nop 0
	v_pk_mul_f32 v[40:41], v[40:41], v[242:243]
	v_pk_mul_f32 v[42:43], v[42:43], v[244:245]
	v_pk_mul_f32 v[40:41], v[56:57], v[40:41]
	v_pk_mul_f32 v[42:43], v[58:59], v[42:43]
	ds_write2_b32 v199, v40, v41 offset0:32 offset1:100
	ds_write2_b32 v199, v42, v43 offset0:168 offset1:236
	v_pk_mul_f32 v[44:45], v[44:45], v[238:239]
	v_pk_mul_f32 v[46:47], v[46:47], v[240:241]
	v_pk_mul_f32 v[60:61], v[60:61], v[238:239]
	v_pk_mul_f32 v[62:63], v[62:63], v[240:241]
	v_mul_f32_e32 v242, 0xbfb8aa3b, v44
	v_mul_f32_e32 v243, 0xbfb8aa3b, v45
	v_mul_f32_e32 v244, 0xbfb8aa3b, v46
	v_mul_f32_e32 v245, 0xbfb8aa3b, v47
	v_exp_f32_e32 v242, v242
	v_exp_f32_e32 v243, v243
	v_exp_f32_e32 v244, v244
	v_exp_f32_e32 v245, v245
	v_add_f32_e32 v242, 1.0, v242
	v_add_f32_e32 v243, 1.0, v243
	v_add_f32_e32 v244, 1.0, v244
	v_add_f32_e32 v245, 1.0, v245
	v_rcp_f32_e32 v242, v242
	v_rcp_f32_e32 v243, v243
	v_rcp_f32_e32 v244, v244
	v_rcp_f32_e32 v245, v245
	s_nop 0
	v_pk_mul_f32 v[44:45], v[44:45], v[242:243]
	v_pk_mul_f32 v[46:47], v[46:47], v[244:245]
	v_pk_mul_f32 v[44:45], v[60:61], v[44:45]
	v_pk_mul_f32 v[46:47], v[62:63], v[46:47]
	ds_write2_b32 v199, v44, v45 offset0:48 offset1:116
	ds_write2_b32 v199, v46, v47 offset0:184 offset1:252
	s_waitcnt lgkmcnt(0)
	ds_read_b128 v[16:19], v200
	ds_read_b128 v[20:23], v200 offset:1088
	ds_read_b128 v[24:27], v200 offset:2176
	ds_read_b128 v[28:31], v200 offset:3264
	ds_read_b128 v[48:51], v200 offset:4352
	ds_read_b128 v[52:55], v200 offset:5440
	ds_read_b128 v[56:59], v200 offset:6528
	ds_read_b128 v[60:63], v200 offset:7616
	s_waitcnt lgkmcnt(7)
	v_lshl_add_u64 v[204:205], v[202:203], 0, s[8:9]
	v_cvt_pk_bf16_f32 v16, v16, v17
	v_cvt_pk_bf16_f32 v17, v18, v19
	s_add_u32 s8, s8, 0x5800
	s_addc_u32 s9, s9, 0
	global_store_dwordx2 v[204:205], v[16:17], off
	s_waitcnt lgkmcnt(6)
	v_lshl_add_u64 v[204:205], v[202:203], 0, s[8:9]
	v_cvt_pk_bf16_f32 v20, v20, v21
	v_cvt_pk_bf16_f32 v21, v22, v23
	s_add_u32 s8, s8, 0x5800
	s_addc_u32 s9, s9, 0
	global_store_dwordx2 v[204:205], v[20:21], off
	s_waitcnt lgkmcnt(5)
	v_lshl_add_u64 v[204:205], v[202:203], 0, s[8:9]
	v_cvt_pk_bf16_f32 v24, v24, v25
	v_cvt_pk_bf16_f32 v25, v26, v27
	s_add_u32 s8, s8, 0x5800
	s_addc_u32 s9, s9, 0
	global_store_dwordx2 v[204:205], v[24:25], off
	s_waitcnt lgkmcnt(4)
	v_lshl_add_u64 v[204:205], v[202:203], 0, s[8:9]
	v_cvt_pk_bf16_f32 v28, v28, v29
	v_cvt_pk_bf16_f32 v29, v30, v31
	s_add_u32 s8, s8, 0x5800
	s_addc_u32 s9, s9, 0
	global_store_dwordx2 v[204:205], v[28:29], off
	s_waitcnt lgkmcnt(3)
	v_lshl_add_u64 v[204:205], v[202:203], 0, s[8:9]
	v_cvt_pk_bf16_f32 v48, v48, v49
	v_cvt_pk_bf16_f32 v49, v50, v51
	s_add_u32 s8, s8, 0x5800
	s_addc_u32 s9, s9, 0
	global_store_dwordx2 v[204:205], v[48:49], off
	s_waitcnt lgkmcnt(2)
	v_lshl_add_u64 v[204:205], v[202:203], 0, s[8:9]
	v_cvt_pk_bf16_f32 v52, v52, v53
	v_cvt_pk_bf16_f32 v53, v54, v55
	s_add_u32 s8, s8, 0x5800
	s_addc_u32 s9, s9, 0
	global_store_dwordx2 v[204:205], v[52:53], off
	s_waitcnt lgkmcnt(1)
	v_lshl_add_u64 v[204:205], v[202:203], 0, s[8:9]
	v_cvt_pk_bf16_f32 v56, v56, v57
	v_cvt_pk_bf16_f32 v57, v58, v59
	s_add_u32 s8, s8, 0x5800
	s_addc_u32 s9, s9, 0
	global_store_dwordx2 v[204:205], v[56:57], off
	s_waitcnt lgkmcnt(0)
	v_lshl_add_u64 v[204:205], v[202:203], 0, s[8:9]
	v_cvt_pk_bf16_f32 v60, v60, v61
	v_cvt_pk_bf16_f32 v61, v62, v63
	s_add_u32 s8, s8, 0x5800
	s_addc_u32 s9, s9, 0
	global_store_dwordx2 v[204:205], v[60:61], off
	s_branch .LBB0_108
